# speedup vs baseline: 1.0812x; 1.0254x over previous
; __device__ __forceinline__ void gemm_tile(const GemmArgs& g, bf16* shm, const int tid, const int wid, char* wsb, const float* gnext) {
;     ...
;     __syncthreads();
;     int t2 = tid; asm volatile("" : "+v"(t2));
;     const char* rd = tl + (t2 >> 5) * 528 + (t2 & 31) * 16;
;     bf16* wr = C + (long)(t2 >> 5) * g.ldc + (t2 & 31) * 8;
;     const long rstep = 16L * g.ldc;
; #pragma unroll
;     for (int i = 0; i < 16; ++i) {
;       const u32x4 w = *reinterpret_cast<const u32x4*>(rd + i * (16 * 528));
;       *reinterpret_cast<u32x4*>(wr + i * rstep) = w;
;     }
; __global__ __launch_bounds__(512, 2)
; void hybrid_megakernel(Params p_in) {
;     ...
;         for (int t = bid; t < ngt; t += G) {
;           const GemmArgs g = load_desc(dt + t);
;           __syncthreads();
;           gemm_tile(g, (bf16*)shm, tid, wid, ws, pp->g_in + (l + 1 < DEPTH ? (l + 1) * DM : 0));
.LBB0_33:
	v_pk_mul_f32 v[0:1], v[18:19], v[2:3] op_sel_hi:[1,0]
	v_pk_mul_f32 v[16:17], v[16:17], v[2:3] op_sel_hi:[1,0]
	v_pk_mul_f32 v[8:9], v[8:9], v[2:3] op_sel_hi:[1,0]
	v_cvt_pk_bf16_f32 v16, v16, v17
	v_cvt_pk_bf16_f32 v17, v0, v1
	ds_write_b64 v69, v[16:17] offset:25344
	v_pk_mul_f32 v[0:1], v[10:11], v[2:3] op_sel_hi:[1,0]
	v_cvt_pk_bf16_f32 v8, v8, v9
	v_pk_mul_f32 v[4:5], v[4:5], v[2:3] op_sel_hi:[1,0]
	v_cvt_pk_bf16_f32 v9, v0, v1
	ds_write_b64 v69, v[8:9] offset:25376
	v_pk_mul_f32 v[0:1], v[14:15], v[2:3] op_sel_hi:[1,0]
	v_pk_mul_f32 v[8:9], v[12:13], v[2:3] op_sel_hi:[1,0]
	s_ashr_i32 s67, s66, 31
	v_cvt_pk_bf16_f32 v8, v8, v9
	v_cvt_pk_bf16_f32 v9, v0, v1
	v_pk_mul_f32 v[0:1], v[6:7], v[2:3] op_sel_hi:[1,0]
	ds_write_b64 v69, v[8:9] offset:25600
	v_cvt_pk_bf16_f32 v4, v4, v5
	v_cvt_pk_bf16_f32 v5, v0, v1
	v_mov_b32_e32 v0, v144
	ds_write_b64 v69, v[4:5] offset:25632
	s_waitcnt vmcnt(0) lgkmcnt(0)
	s_barrier
	s_nop 0
	v_ashrrev_i32_e32 v1, 5, v0
	v_lshlrev_b32_e32 v0, 4, v0
	v_mul_lo_u32 v4, v1, s31
	v_and_b32_e32 v2, 0x1f0, v0
	v_add3_u32 v8, 0, v4, v2
	v_add_u32_e32 v9, 0x10800, v8
	ds_read_b128 v[12:15], v8
	ds_read_b128 v[16:19], v8 offset:8448
	ds_read_b128 v[20:23], v8 offset:16896
	ds_read_b128 v[24:27], v8 offset:25344
	ds_read_b128 v[28:31], v8 offset:33792
	ds_read_b128 v[32:35], v8 offset:42240
	ds_read_b128 v[36:39], v8 offset:50688
	ds_read_b128 v[40:43], v8 offset:59136
	ds_read_b128 v[44:47], v9
	ds_read_b128 v[48:51], v9 offset:8448
	ds_read_b128 v[52:55], v9 offset:16896
	ds_read_b128 v[56:59], v9 offset:25344
	ds_read_b128 v[60:63], v9 offset:33792
	ds_read_b128 v[64:67], v9 offset:42240
	ds_read_b128 v[68:71], v9 offset:50688
	ds_read_b128 v[72:75], v9 offset:59136
	v_mul_lo_u32 v10, v1, s66
	v_lshl_add_u32 v10, v10, 1, v2
	s_lshl_b32 s0, s66, 5
	s_mov_b32 s2, s68
	s_mov_b32 s3, s69
	s_waitcnt lgkmcnt(15)
	global_store_dwordx4 v10, v[12:15], s[2:3]
	s_add_u32 s2, s2, s0
	s_addc_u32 s3, s3, 0
	s_waitcnt lgkmcnt(14)
	global_store_dwordx4 v10, v[16:19], s[2:3]
	s_add_u32 s2, s2, s0
	s_addc_u32 s3, s3, 0
	s_waitcnt lgkmcnt(13)
	global_store_dwordx4 v10, v[20:23], s[2:3]
	s_add_u32 s2, s2, s0
	s_addc_u32 s3, s3, 0
	s_waitcnt lgkmcnt(12)
	global_store_dwordx4 v10, v[24:27], s[2:3]
	s_add_u32 s2, s2, s0
	s_addc_u32 s3, s3, 0
	s_waitcnt lgkmcnt(11)
	global_store_dwordx4 v10, v[28:31], s[2:3]
	s_add_u32 s2, s2, s0
	s_addc_u32 s3, s3, 0
	s_waitcnt lgkmcnt(10)
	global_store_dwordx4 v10, v[32:35], s[2:3]
	s_add_u32 s2, s2, s0
	s_addc_u32 s3, s3, 0
	s_waitcnt lgkmcnt(9)
	global_store_dwordx4 v10, v[36:39], s[2:3]
	s_add_u32 s2, s2, s0
	s_addc_u32 s3, s3, 0
	s_waitcnt lgkmcnt(8)
	global_store_dwordx4 v10, v[40:43], s[2:3]
	s_add_u32 s2, s2, s0
	s_addc_u32 s3, s3, 0
	s_waitcnt lgkmcnt(7)
	global_store_dwordx4 v10, v[44:47], s[2:3]
	s_add_u32 s2, s2, s0
	s_addc_u32 s3, s3, 0
	s_waitcnt lgkmcnt(6)
	global_store_dwordx4 v10, v[48:51], s[2:3]
	s_add_u32 s2, s2, s0
	s_addc_u32 s3, s3, 0
	s_waitcnt lgkmcnt(5)
	global_store_dwordx4 v10, v[52:55], s[2:3]
	s_add_u32 s2, s2, s0
	s_addc_u32 s3, s3, 0
	s_waitcnt lgkmcnt(4)
	global_store_dwordx4 v10, v[56:59], s[2:3]
	s_add_u32 s2, s2, s0
	s_addc_u32 s3, s3, 0
	s_waitcnt lgkmcnt(3)
	global_store_dwordx4 v10, v[60:63], s[2:3]
	s_add_u32 s2, s2, s0
	s_addc_u32 s3, s3, 0
	s_waitcnt lgkmcnt(2)
	global_store_dwordx4 v10, v[64:67], s[2:3]
	s_add_u32 s2, s2, s0
	s_addc_u32 s3, s3, 0
	s_waitcnt lgkmcnt(1)
	global_store_dwordx4 v10, v[68:71], s[2:3]
	s_add_u32 s2, s2, s0
	s_addc_u32 s3, s3, 0
	s_waitcnt lgkmcnt(0)
	global_store_dwordx4 v10, v[72:75], s[2:3]
.LBB0_34:
	s_add_i32 s8, s8, s52
	s_cmp_ge_i32 s8, s38
	s_cbranch_scc1 .LBB0_94
	s_waitcnt lgkmcnt(0)
	v_mov_b32_e32 v4, s84
	v_mov_b32_e32 v5, s85
	v_mov_b32_e32 v6, s86
	v_mov_b32_e32 v7, s87
	v_mov_b32_e32 v16, s88
	v_mov_b32_e32 v17, s89
	v_mov_b32_e32 v18, s90
	v_mov_b32_e32 v19, s91
	v_mov_b32_e32 v8, s92
	v_mov_b32_e32 v9, s93
	v_mov_b32_e32 v10, s94
	v_mov_b32_e32 v11, s95
	v_mov_b32_e32 v12, s96
	v_mov_b32_e32 v13, s97
	v_mov_b32_e32 v14, s98
	v_mov_b32_e32 v15, s99
	s_add_i32 s75, s26, 0x10000
	s_branch .Ltile_join

; #define STAGE_A(P, half, kt) do { const char* _p = Ab + (half) * aH + (long)(kt) * (BK * 2);                           \
;     __builtin_amdgcn_global_load_lds((const unsigned*)(_p + voA), (unsigned*)((char*)(P) + wid * 1024), 16, 0, 0);         \
;     __builtin_amdgcn_global_load_lds((const unsigned*)(_p + a64 + voA), (unsigned*)((char*)(P) + wid * 1024 + 8192), 16, 0, 0); } while (0)
; #define STAGE_B(P, half, kt) do { const char* _p = Bb + (half) * bH + (long)(kt) * (BK * 2);                           \
;     __builtin_amdgcn_global_load_lds((const unsigned*)(_p + voB), (unsigned*)((char*)(P) + wid * 1024), 16, 0, 0);         \
;     __builtin_amdgcn_global_load_lds((const unsigned*)(_p + b64 + voB), (unsigned*)((char*)(P) + wid * 1024 + 8192), 16, 0, 0); } while (0)
; #define WAIT_V(n) asm volatile("s_waitcnt vmcnt(" #n ")" ::: "memory")
; #define BAR __builtin_amdgcn_s_barrier()
; __device__ __forceinline__ void gemm_tile(const GemmArgs& g, bf16* shm, const int tid, const int wid, char* wsb, const float* gnext) {
;     ...
;   STAGE_B(SB(0, 0), 0, 0); STAGE_A(SA(0, 0), 0, 0);
;   STAGE_B(SB(0, 1), 1, 0); STAGE_A(SA(0, 1), 1, 0);
;   if (wr == 1) BAR;
;   WAIT_V(4); BAR;
.Ltile_join:
	s_mov_b32 m0, s75
	s_barrier
	s_waitcnt vmcnt(0)
	v_readfirstlane_b32 s10, v6
	s_waitcnt vmcnt(2)
	v_readfirstlane_b32 s2, v8
	v_readfirstlane_b32 s16, v9
	s_ashr_i32 s3, s2, 31
	s_ashr_i32 s17, s16, 31
	s_lshl_b64 s[6:7], s[2:3], 7
	s_lshl_b64 s[14:15], s[16:17], 7
	v_readfirstlane_b32 s11, v7
	s_add_u32 s28, s10, s14
	v_readfirstlane_b32 s0, v4
	s_addc_u32 s29, s11, s15
	s_add_i32 s77, s26, 0x12000
	v_readfirstlane_b32 s1, v5
	s_add_u32 s66, s0, s6
	s_addc_u32 s67, s1, s7
	s_add_i32 s84, s26, 0x2000
	v_mul_lo_u32 v1, s16, v145
	s_add_u32 s48, s28, s14
	s_waitcnt lgkmcnt(0)
	v_add_lshl_u32 v2, v1, v150, 1
	s_addc_u32 s49, s29, s15
	s_add_i32 s85, s26, 0x14000
	v_mul_lo_u32 v0, s2, v145
	global_load_lds_dwordx4 v2, s[10:11]
	s_mov_b32 m0, s77
	s_add_u32 s50, s48, s14
	v_add_lshl_u32 v0, v0, v150, 1
	global_load_lds_dwordx4 v2, s[28:29]
	s_mov_b32 m0, s26
	s_addc_u32 s51, s49, s15
	s_add_i32 s86, s26, 0x16000
	global_load_lds_dwordx4 v0, s[0:1]
	s_mov_b32 m0, s84
	s_add_u32 s72, s66, s6
	global_load_lds_dwordx4 v0, s[66:67]
	s_mov_b32 m0, s85
	s_addc_u32 s73, s67, s7
	s_add_i32 s87, s26, 0x4000
	global_load_lds_dwordx4 v2, s[48:49]
	s_mov_b32 m0, s86
	s_add_u32 s28, s72, s6
	global_load_lds_dwordx4 v2, s[50:51]
	s_mov_b32 m0, s87
	s_addc_u32 s29, s73, s7
	s_add_i32 s88, s26, 0x6000
	global_load_lds_dwordx4 v0, s[72:73]
	s_mov_b32 m0, s88
	s_waitcnt vmcnt(0)
	v_readfirstlane_b32 s69, v17
	global_load_lds_dwordx4 v0, s[28:29]
	v_readlane_b32 s28, v255, 7
	v_readlane_b32 s29, v255, 8
	v_readfirstlane_b32 s68, v16
	v_readfirstlane_b32 s71, v19
	v_readfirstlane_b32 s70, v18
	v_readfirstlane_b32 s66, v10
	v_readfirstlane_b32 s67, v11
	v_readfirstlane_b32 s89, v12
	v_readfirstlane_b32 s9, v13
	v_readfirstlane_b32 s74, v14
	s_andn2_b64 vcc, exec, s[28:29]
	v_readfirstlane_b32 s83, v15
	s_cbranch_vccnz .LBB0_37
	s_barrier

; __device__ __forceinline__ void gemm_tile(const GemmArgs& g, bf16* shm, const int tid, const int wid, char* wsb, const float* gnext) {
;     ...
;   if (g.epi == EPI_BF16 || g.epi == EPI_BF16_RS) {
;     bf16* C = (bf16*)g.C; const float* rss = (const float*)g.X; const bool rsc = (g.epi == EPI_BF16_RS);
; __global__ __launch_bounds__(512, 2)
; void hybrid_megakernel(Params p_in) {
;     ...
;         for (int t = bid; t < ngt; t += G) {
;           const GemmArgs g = load_desc(dt + t);
.LBB0_42:
	s_add_i32 s0, s8, s52
	s_ashr_i32 s1, s0, 31
	s_lshl_b64 s[0:1], s[0:1], 6
	s_add_u32 s0, s57, s0
	s_addc_u32 s1, s61, s1
	s_load_dwordx16 s[84:99], s[0:1], 0x0
	v_mov_b32_e32 v132, v157
	v_mov_b32_e32 v0, v152
	s_cmp_lt_i32 s9, 2
	s_cbranch_scc1 .LBB0_46
	s_cmp_gt_i32 s9, 3
	s_cbranch_scc0 .LBB0_47
	s_cmp_gt_i32 s9, 4
	s_cbranch_scc0 .LBB0_48
	s_cmp_lg_u32 s9, 5
	s_mov_b64 s[6:7], -1
	s_cselect_b64 s[72:73], -1, 0
	s_cbranch_execz .LBB0_49
	s_branch .LBB0_66

; __device__ __forceinline__ unsigned rfl(unsigned v) { return (unsigned)__builtin_amdgcn_readfirstlane((int)v); }
; __global__ __launch_bounds__(512, 2)
; void hybrid_megakernel(Params p_in) {
;     ...
;           const float slope = exp2f(-(float)(h + 1));
;           const float q2 = __uint_as_float(rfl(nrm[b * 32 + h * 2 + c])), k2 = __uint_as_float(rfl(nrm[b * 32 + 16 + h * 2 + c]));
;           const float Bnd = sqrtf(q2 * k2) * ASCALE * 1.002f + 0.05f;
;           const float nsf = __uint_as_float(rfl(((const unsigned*)(ws + WS_NRM))[144 + l * (NB * 16) + b * 16 + h * 2 + c]));
;           const float lowb = fminf(nsf * ASCALE * 1.002f + 0.05f, Bnd);
.LBB0_157:
	s_sub_i32 s0, 8, s8
	v_cvt_f32_i32_e32 v0, s0
	s_mov_b32 s0, 0x42fc0000
	v_mov_b32_e32 v1, 0x42800000
	s_and_b32 s63, s9, 1
	v_cmp_lt_f32_e32 vcc, s0, v0
	s_sub_i32 s1, 7, s8
	s_and_b64 s[8:9], vcc, exec
	v_cndmask_b32_e32 v1, 0, v1, vcc
	v_sub_f32_e32 v0, v1, v0
	v_exp_f32_e32 v0, v0
	s_cselect_b32 s0, 0xffffffc0, 0
	s_lshl_b32 s3, s1, 1
	v_mov_b32_e32 v153, v3
	v_ldexp_f32 v0, v0, s0
	s_lshl_b32 s0, s38, 5
	s_add_i32 s0, s0, s3
	s_or_b32 s8, s0, s63
	s_ashr_i32 s9, s8, 31
	s_lshl_b64 s[28:29], s[8:9], 2
	s_add_u32 s28, s48, s28
	s_addc_u32 s29, s49, s29
	global_load_dword v1, v3, s[28:29]
	s_ashr_i32 s9, s0, 31
	s_lshl_b64 s[8:9], s[8:9], 2
	s_add_u32 s8, s48, s8
	s_addc_u32 s9, s49, s9
	v_mov_b32_e32 v157, v3
	s_movk_i32 s95, 0x6000
	s_waitcnt vmcnt(0)
	v_readfirstlane_b32 s28, v1
	global_load_dword v1, v3, s[8:9] offset:64
	s_waitcnt vmcnt(0)
	v_readfirstlane_b32 s0, v1
	s_nop 1
	v_mov_b32_e32 v1, s0
	v_mul_f32_e32 v1, s28, v1
	s_mov_b32 s0, 0xf800000
	v_cmp_gt_f32_e32 vcc, s0, v1
	v_mul_f32_e32 v2, 0x4f800000, v1
	s_lshl_b32 s0, s38, 4
	v_cndmask_b32_e32 v1, v1, v2, vcc
	v_sqrt_f32_e32 v2, v1
	s_add_i32 s0, s56, s0
	s_add_i32 s0, s0, s3
	v_add_u32_e32 v4, -1, v2
	v_fma_f32 v5, -v4, v2, v1
	v_cmp_ge_f32_e64 s[8:9], 0, v5
	v_add_u32_e32 v5, 1, v2
	s_nop 0
	v_cndmask_b32_e64 v4, v2, v4, s[8:9]
	v_fma_f32 v2, -v5, v2, v1
	v_cmp_lt_f32_e64 s[8:9], 0, v2
	s_nop 1
	v_cndmask_b32_e64 v2, v4, v5, s[8:9]
	v_mul_f32_e32 v4, 0x37800000, v2
	s_or_b32 s8, s0, s63
	v_cndmask_b32_e32 v2, v2, v4, vcc
	v_mov_b32_e32 v4, 0x260
	s_ashr_i32 s9, s8, 31
	v_cmp_class_f32_e32 vcc, v1, v4
	s_lshl_b64 s[8:9], s[8:9], 2
	s_add_u32 s8, s16, s8
	v_cndmask_b32_e32 v1, v2, v1, vcc
	v_mul_f32_e32 v1, 0x3db504f3, v1
	s_addc_u32 s9, s17, s9
	v_fmamk_f32 v20, v1, 0x3f804189, v195
	s_barrier
; __device__ __forceinline__ void attn_body3(const bf16* __restrict__ Qb, const bf16* __restrict__ Kh, const bf16* __restrict__ Vh,
;                                            bf16* __restrict__ Ob, int seq, int qpos0, float slS, float mraw, char* lds, const int tid) {
;   const int wid = __builtin_amdgcn_readfirstlane(tid >> 6), lane = tid & 63, r32 = lane & 31, hi = lane >> 5;
;   const int pair = wid & 3, role = wid >> 2;
;   constexpr float C = ASCALE * 1.4426950408889634f;
;   f32x16 o[4] = {}; bf16x8 qr[8]; float lsum = 0.f;
;   const int qw0 = qpos0 + pair * QBLK;
;   const float qposf = (float)(qw0 + r32), hi4 = 4.f * (float)hi + 32.f * (float)role;
;   unsigned qa0, qa1, kj0;
;   { const float a1 = bf_lo(cvtpk(slS, 0.f) & 0xffffu), r1 = slS - a1, a2 = bf_lo(cvtpk(r1, 0.f) & 0xffffu), a3 = r1 - a2;
;     const unsigned u12 = cvtpk(a1, a2), u3 = cvtpk(a3, 0.f) & 0xffffu;
;     const unsigned j0 = __float_as_uint((float)(r32 + 32 * role)) >> 16;
;     qa0 = hi ? 0u : u12; qa1 = hi ? 0u : u3; kj0 = hi ? 0u : (j0 | (j0 << 16)); }
;   { const unsigned qoff = (unsigned)((pair * QBLK + r32) * LDQ + hi * 8) * 2u;
; #pragma unroll
;     for (int d0 = 0; d0 < 8; ++d0) qr[d0] = *reinterpret_cast<const bf16x8*>((const char*)Qb + qoff + d0 * 32); }
;   const int vb0 = (int)(uintptr_t)(lds + A3_V) + role * 16384 + v_rd_base(lane);
; __global__ __launch_bounds__(512, 2)
; void hybrid_megakernel(Params p_in) {
;     ...
;           const float Wn = (Bnd + lowb + 104.f) / slope;
;           int t_lo = (int)floorf(fmaxf((float)(qb * 128) - Wn, 0.f) * (1.f / 64.f)) & ~1;
;           int t_hi = (int)fminf(((float)(qb * 128 + 127) + Wn) * (1.f / 64.f) + 1.f, (float)(SEQ / KVBLK));
;           t_hi = min((t_hi + 1) & ~1, SEQ / KVBLK);
;           t_lo = __builtin_amdgcn_readfirstlane(t_lo); t_hi = __builtin_amdgcn_readfirstlane(t_hi);
;           const bf16* Qb = proj + ((long)b * SEQ + qb * 128) * INC + OFF_Q + h * 256 + c * 128;
;           const bf16* Kh = proj + ((long)b * SEQ + t_lo * KVBLK) * INC + OFF_K + h * 256 + c * 128;
;           const bf16* Vh = proj + ((long)b * SEQ + t_lo * KVBLK) * INC + OFF_V + h * 256;
;           bf16* Ob = (bf16*)attO + (long)c * NTOK * 2048 + ((long)b * SEQ + qb * 128) * 2048 + h * 256;
;           __syncthreads();
;           attn_body3(Qb, Kh, Vh, Ob, (t_hi - t_lo) * KVBLK, qb * 128 - t_lo * KVBLK, slope / ASCALE, Bnd / ASCALE, shm, tid);
	s_waitcnt vmcnt(0)
	v_mov_b32_e32 v1, 0x42b20000
	v_div_scale_f32 v2, s[8:9], v0, v0, v1
	v_rcp_f32_e32 v4, v2
	s_lshl_b32 s0, s2, 7
	s_or_b32 s2, s0, 0x7f
	s_lshl_b64 s[8:9], s[38:39], 13
	v_fma_f32 v5, -v2, v4, 1.0
	v_fmac_f32_e32 v4, v5, v4
	v_div_scale_f32 v5, vcc, v1, v0, v1
	v_mul_f32_e32 v6, v5, v4
	v_fma_f32 v7, -v2, v6, v5
	v_fmac_f32_e32 v6, v7, v4
	v_fma_f32 v2, -v2, v6, v5
	v_div_fmas_f32 v2, v2, v4, v6
	v_div_fixup_f32 v1, v2, v0, v1
	v_cvt_f32_u32_e32 v2, s0
	v_cvt_f32_u32_e32 v4, s2
	s_mov_b32 s2, 0x3c800000
	v_sub_f32_e32 v2, v2, v1
	v_max_f32_e32 v2, 0, v2
	v_mul_f32_e32 v2, 0x3c800000, v2
	v_floor_f32_e32 v2, v2
	v_add_f32_e32 v1, v1, v4
	v_fma_f32 v1, v1, s2, 1.0
	v_readfirstlane_b32 s2, v2
	v_min_f32_e32 v1, 0x43000000, v1
	v_cvt_i32_f32_e32 v1, v1
	v_cvt_i32_f32_e32 v2, s2
	v_add_u32_e32 v1, 1, v1
	v_readfirstlane_b32 s2, v2
	s_and_b32 s28, s2, -2
	s_add_u32 s70, s8, s0
	s_addc_u32 s71, s9, 0
	s_mul_i32 s2, s71, 0x6000
	s_mul_hi_u32 s3, s70, 0x6000
	s_add_i32 s3, s3, s2
	s_mul_i32 s2, s70, 0x6000
	s_add_u32 s38, s10, s2
	s_addc_u32 s74, s11, s3
	s_lshl_b32 s2, s1, 8
	s_ashr_i32 s3, s2, 31
	s_lshl_b64 s[72:73], s[2:3], 1
	s_add_u32 s1, s38, s72
	s_addc_u32 s3, s74, s73
	s_lshl_b32 s38, s63, 8
	s_add_u32 s2, s1, s38
	s_addc_u32 s3, s3, 0
	s_lshl_b32 s1, s28, 6
	s_ashr_i32 s74, s1, 31
	s_add_u32 s8, s8, s1
	s_addc_u32 s9, s9, s74
	s_mulk_i32 s9, 0x6000
	s_mul_hi_u32 s74, s8, 0x6000
	s_add_i32 s74, s74, s9
	s_mulk_i32 s8, 0x6000
	s_add_u32 s8, s10, s8
	s_addc_u32 s9, s11, s74
	s_add_u32 s8, s8, s72
	s_addc_u32 s9, s9, s73
	s_add_u32 s38, s8, s38
	s_addc_u32 s75, s9, 0
	v_and_b32_e32 v1, -2, v1
	s_add_u32 s74, s38, 0x1000
	v_min_i32_e32 v1, 0x80, v1
	s_addc_u32 s75, s75, 0
	v_readfirstlane_b32 s29, v1
	s_add_u32 s76, s8, 0x2000
	s_addc_u32 s77, s9, 0
	s_sub_i32 s80, s29, s28
	s_mov_b32 s28, 0x3db504f3
	v_div_scale_f32 v1, s[8:9], s28, s28, v0
	v_rcp_f32_e32 v2, v1
	v_readfirstlane_b32 s8, v144
	s_ashr_i32 s79, s8, 6
	s_and_b32 s81, s79, 3
	v_fma_f32 v4, -v1, v2, 1.0
	v_fmac_f32_e32 v2, v4, v2
	v_div_scale_f32 v4, vcc, v0, s28, v0
	v_mul_f32_e32 v5, v4, v2
	v_fma_f32 v6, -v1, v5, v4
	v_fmac_f32_e32 v5, v6, v2
	v_fma_f32 v1, -v1, v5, v4
	v_div_fmas_f32 v1, v1, v2, v5
	v_div_fixup_f32 v148, v1, s28, v0
	v_cvt_pk_bf16_f32 v0, v148, v3
	s_lshl_b32 s78, s81, 5
	v_lshlrev_b32_e32 v0, 16, v0
	v_sub_f32_e32 v1, v148, v0
	v_cvt_pk_bf16_f32 v2, v1, v3
	s_ashr_i32 s38, s8, 8
	v_lshlrev_b32_e32 v2, 16, v2
	v_sub_f32_e32 v1, v1, v2
	v_cvt_pk_bf16_f32 v0, v0, v2
	v_or_b32_e32 v2, s78, v149
	v_mul_u32_u24_e32 v2, 0x6000, v2
	v_or_b32_e32 v2, v2, v165
	v_cvt_pk_bf16_f32 v1, v1, v3
	global_load_dwordx4 v[96:99], v2, s[2:3]
	global_load_dwordx4 v[100:103], v2, s[2:3] offset:32
	global_load_dwordx4 v[104:107], v2, s[2:3] offset:64
	global_load_dwordx4 v[108:111], v2, s[2:3] offset:96
	global_load_dwordx4 v[112:115], v2, s[2:3] offset:128
	global_load_dwordx4 v[116:119], v2, s[2:3] offset:160
	global_load_dwordx4 v[120:123], v2, s[2:3] offset:192
	global_load_dwordx4 v[124:127], v2, s[2:3] offset:224
	s_lshl_b32 s2, s79, 7
	v_or_b32_e32 v2, s2, v145
	s_ashr_i32 s2, s2, 4
	s_and_b32 s3, s2, 0x7fff0
	s_lshr_b32 s2, s2, 1
	v_or_b32_e32 v4, s3, v174
	v_and_or_b32 v4, s2, 4, v4
	v_ashrrev_i32_e32 v5, 4, v2
	s_movk_i32 s2, 0x6000
	v_mul_lo_u32 v6, v5, s2
	v_bitop3_b32 v5, v5, v173, 3 bitop3:0x6c
	v_or_b32_e32 v2, 64, v2
	v_lshl_or_b32 v150, v5, 4, v6
	v_ashrrev_i32_e32 v5, 4, v2
	v_mul_lo_u32 v6, v5, s2
	s_movk_i32 s2, 0x60
	v_and_or_b32 v2, v2, s2, v175
	s_lshl_b32 s2, s79, 11
	s_add_i32 s83, s2, 0
	s_add_i32 s84, s83, 0x18000
	v_bitop3_b32 v5, v5, v173, 7 bitop3:0x6c
	s_mov_b32 m0, s84
	s_add_i32 s85, s83, 0x18400
	v_mul_u32_u24_e32 v4, 0x6000, v4
	v_lshl_or_b32 v154, v5, 4, v6
	global_load_lds_dwordx4 v150, s[74:75]
	s_mov_b32 m0, s85
	v_or_b32_e32 v152, v4, v176
	global_load_lds_dwordx4 v154, s[74:75]
	s_mov_b32 m0, s83
	v_lshl_or_b32 v156, v2, 1, v4
	v_lshl_add_u64 v[4:5], s[76:77], 0, v[152:153]
	global_load_lds_dwordx4 v152, s[76:77]
	s_add_i32 m0, s83, 0x400
	v_lshl_add_u64 v[6:7], s[76:77], 0, v[156:157]
	global_load_lds_dwordx4 v156, s[76:77]
	v_lshl_add_u64 v[4:5], v[4:5], 0, s[42:43]
	s_add_i32 m0, s83, 0x4000
	s_lshl_b32 s82, s38, 5
	global_load_lds_dwordx4 v[4:5], off
	v_lshl_add_u64 v[4:5], v[6:7], 0, s[42:43]
	s_add_i32 m0, s83, 0x4400
	v_or_b32_e32 v147, s82, v149
	global_load_lds_dwordx4 v[4:5], off
	s_waitcnt vmcnt(0)
	v_lshl_add_u32 v179, s81, 12, v168
	v_lshl_add_u32 v180, s38, 14, v167
	s_cmp_lt_i32 s80, 1
	s_waitcnt vmcnt(0) lgkmcnt(0)
	s_barrier
	s_cbranch_scc1 .LBB0_186
	v_mov_b32_e32 v151, v3
	v_mov_b32_e32 v155, v3
	s_lshl_b32 s29, s80, 6
	s_cmpk_lt_u32 s29, 0x80
	s_cbranch_scc1 .LBB0_160
	s_add_u32 s2, s76, 0x180000
	s_addc_u32 s3, s77, 0
	s_add_u32 s8, s74, 0x180000
	s_addc_u32 s9, s75, 0
	v_lshl_add_u64 v[4:5], s[8:9], 0, v[150:151]
	s_add_i32 m0, s83, 0x1c000
	s_nop 0
	global_load_lds_dwordx4 v[4:5], off
	v_lshl_add_u64 v[4:5], s[8:9], 0, v[154:155]
	s_add_i32 m0, s83, 0x1c400
	s_nop 0
	global_load_lds_dwordx4 v[4:5], off
	v_lshl_add_u64 v[4:5], s[2:3], 0, v[152:153]
	s_add_i32 m0, s83, 0x8000
	s_nop 0
	global_load_lds_dwordx4 v[4:5], off
	s_add_i32 m0, s83, 0x8400
	v_lshl_add_u64 v[4:5], s[2:3], 0, v[156:157]
	s_add_u32 s2, s76, 0x180100
	s_addc_u32 s3, s77, 0
	global_load_lds_dwordx4 v[4:5], off
	v_lshl_add_u64 v[4:5], s[2:3], 0, v[152:153]
	s_add_i32 m0, s83, 0xc000
	s_nop 0
	global_load_lds_dwordx4 v[4:5], off
	v_lshl_add_u64 v[4:5], s[2:3], 0, v[156:157]
	s_add_i32 m0, s83, 0xc400
	s_nop 0
	global_load_lds_dwordx4 v[4:5], off
